# P4: eight late mixer workgroups (one per XCD) start the L2 write-back when they finish, ahead of the closing barrier
# speedup vs baseline: 1.0064x; 1.0064x over previous
.LBB0_564:
	s_sub_u32 s98, s74, 32
	s_cmp_lt_u32 s98, 8
	s_cbranch_scc0 .Lp4_nowb
	v_readlane_b32 s98, v211, 0
	s_cmp_lt_u32 s98, 64
	s_cbranch_scc0 .Lp4_nowb
	s_waitcnt vmcnt(0)
	buffer_wbl2 sc1
